# attention tile loop: first four P.V MFMAs hoisted above the row-max chain, post-barrier segment leads with an MFMA (loads and K-fragment reads fed through later gaps), counted waits re-derived
# speedup vs baseline: 1.0581x; 1.0116x over previous
.LBB0_458:
	s_waitcnt vmcnt(3)
	ds_write_b128 v243, v[112:115]
	s_waitcnt vmcnt(2)
	ds_write_b128 v243, v[116:119] offset:9216
	v_add_u32_e32 v112, s17, v242
	v_add_u32_e32 v177, s16, v246
	s_waitcnt vmcnt(1)
	ds_write_b128 v112, v[120:123] offset:36864
	s_waitcnt vmcnt(0)
	ds_write_b128 v112, v[124:127] offset:47104
	s_waitcnt lgkmcnt(11)
	v_mfma_f32_32x32x16_bf16 v[128:143], v[220:223], v[156:159], v[64:79]
	v_add_f32_e32 v112, v96, v98
	v_add_f32_e32 v113, v97, v99
	v_add_f32_e32 v112, v100, v112
	v_add_f32_e32 v113, v101, v113
	v_cvt_pk_bf16_f32 v160, v96, v97
	v_cvt_pk_bf16_f32 v161, v98, v99
	s_nop 0
	v_add_f32_e32 v96, v102, v112
	v_add_f32_e32 v97, v103, v113
	s_waitcnt lgkmcnt(9)
	v_mfma_f32_32x32x16_bf16 v[112:127], v[216:219], v[156:159], v[64:79]
	v_add_f32_e32 v96, v104, v96
	v_add_f32_e32 v97, v105, v97
	v_cvt_pk_bf16_f32 v162, v100, v101
	v_cvt_pk_bf16_f32 v163, v102, v103
	v_mfma_f32_32x32x16_bf16 v[128:143], v[212:215], v[152:155], v[128:143]
	v_add_f32_e32 v96, v106, v96
	v_add_f32_e32 v97, v107, v97
	v_add_f32_e32 v96, v108, v96
	v_add_f32_e32 v97, v109, v97
	v_cvt_pk_bf16_f32 v164, v104, v105
	v_cvt_pk_bf16_f32 v165, v106, v107
	s_waitcnt lgkmcnt(8)
	v_mfma_f32_32x32x16_bf16 v[112:127], v[208:211], v[152:155], v[112:127]
	v_add_f32_e32 v96, v110, v96
	v_add_f32_e32 v97, v111, v97
	v_add_f32_e32 v96, v80, v96
	v_add_f32_e32 v97, v81, v97
	v_cvt_pk_bf16_f32 v166, v108, v109
	v_cvt_pk_bf16_f32 v167, v110, v111
	s_waitcnt lgkmcnt(7)
	v_mfma_f32_32x32x16_bf16 v[128:143], v[204:207], v[148:151], v[128:143]
	ds_read_b64_tr_b16 v[220:221], v177 offset:36864
	ds_read_b64_tr_b16 v[222:223], v177 offset:39424
	v_add_f32_e32 v96, v82, v96
	v_add_f32_e32 v97, v83, v97
	v_add_f32_e32 v96, v84, v96
	v_add_f32_e32 v97, v85, v97
	v_cvt_pk_bf16_f32 v168, v80, v81
	v_cvt_pk_bf16_f32 v169, v82, v83
	s_waitcnt lgkmcnt(7)
	v_mfma_f32_32x32x16_bf16 v[112:127], v[200:203], v[148:151], v[112:127]
	ds_read_b64_tr_b16 v[108:109], v177 offset:36928
	ds_read_b64_tr_b16 v[110:111], v177 offset:39488
	v_add_f32_e32 v80, v86, v96
	v_add_f32_e32 v81, v87, v97
	v_add_f32_e32 v80, v88, v80
	v_add_f32_e32 v81, v89, v81
	v_cvt_pk_bf16_f32 v170, v84, v85
	v_cvt_pk_bf16_f32 v171, v86, v87
	v_mfma_f32_32x32x16_bf16 v[128:143], v[196:199], v[144:147], v[128:143]
	ds_read_b64_tr_b16 v[104:105], v177 offset:36992
	ds_read_b64_tr_b16 v[106:107], v177 offset:39552
	v_add_f32_e32 v80, v90, v80
	v_add_f32_e32 v81, v91, v81
	v_add_f32_e32 v80, v92, v80
	v_add_f32_e32 v81, v93, v81
	v_cvt_pk_bf16_f32 v172, v88, v89
	v_cvt_pk_bf16_f32 v173, v90, v91
	s_waitcnt lgkmcnt(10)
	v_mfma_f32_32x32x16_bf16 v[112:127], v[192:195], v[144:147], v[112:127]
	ds_read_b64_tr_b16 v[100:101], v177 offset:37056
	ds_read_b64_tr_b16 v[102:103], v177 offset:39616
	v_add_f32_e32 v80, v94, v80
	v_add_f32_e32 v81, v95, v81
	v_add_f32_e32 v80, 0, v80
	v_add_f32_e32 v81, 0, v81
	v_cvt_pk_bf16_f32 v174, v92, v93
	v_cvt_pk_bf16_f32 v175, v94, v95
	s_nop 0
	v_add_f32_e32 v80, v80, v81
	v_add_f32_e32 v247, v247, v80
	s_waitcnt lgkmcnt(6)
	v_mfma_f32_32x32x16_bf16 v[0:15], v[220:223], v[160:163], v[0:15]
	ds_read_b64_tr_b16 v[220:221], v177 offset:41984
	ds_read_b64_tr_b16 v[222:223], v177 offset:44544
	v_max3_f32 v81, v128, v129, v112
	v_max3_f32 v82, v130, v131, v113
	v_max3_f32 v81, v81, v114, v115
	v_max3_f32 v82, v82, v134, v135
	v_max3_f32 v81, v81, v132, v133
	s_waitcnt lgkmcnt(6)
	v_mfma_f32_32x32x16_bf16 v[48:63], v[108:111], v[160:163], v[48:63]
	ds_read_b64_tr_b16 v[108:109], v177 offset:42048
	ds_read_b64_tr_b16 v[110:111], v177 offset:44608
	v_max3_f32 v82, v82, v118, v119
	v_max3_f32 v81, v81, v116, v117
	v_max3_f32 v82, v82, v138, v139
	v_max3_f32 v81, v81, v136, v137
	s_waitcnt lgkmcnt(6)
	v_mfma_f32_32x32x16_bf16 v[32:47], v[104:107], v[160:163], v[32:47]
	ds_read_b64_tr_b16 v[104:105], v177 offset:42112
	ds_read_b64_tr_b16 v[106:107], v177 offset:44672
	v_max3_f32 v82, v82, v122, v123
	v_max3_f32 v81, v81, v120, v121
	v_max3_f32 v82, v82, v142, v143
	v_max3_f32 v81, v81, v140, v141
	s_waitcnt lgkmcnt(6)
	v_mfma_f32_32x32x16_bf16 v[16:31], v[100:103], v[160:163], v[16:31]
	ds_read_b64_tr_b16 v[100:101], v177 offset:42176
	ds_read_b64_tr_b16 v[102:103], v177 offset:44736
	v_max3_f32 v82, v82, v126, v127
	v_max3_f32 v81, v81, v124, v125
	v_max_f32_e32 v80, v81, v82
	v_mov_b32_e32 v81, v80
	s_nop 1
	v_permlane32_swap_b32_e32 v80, v81
	v_max_f32_e32 v80, v80, v81
	v_cmp_lt_f32_e32 vcc, s61, v80
	s_cbranch_vccnz .LBB0_466
	v_mov_b32_e32 v176, 1.0
.LBB0_460:
	s_sub_i32 s18, s4, 64
	s_and_b32 s18, s18, 0x7c0
	s_mul_i32 s70, s18, 0x2800
	v_lshl_add_u64 v[88:89], v[226:227], 0, s[70:71]
	s_waitcnt lgkmcnt(0)
	s_barrier
	s_setprio 1
	v_mfma_f32_32x32x16_bf16 v[0:15], v[220:223], v[164:167], v[0:15]
	ds_read_b64_tr_b16 v[220:221], v177 offset:47104
	ds_read_b64_tr_b16 v[222:223], v177 offset:49664
	v_exp_f32_e32 v128, v128
	v_exp_f32_e32 v129, v129
	v_exp_f32_e32 v130, v130
	v_lshl_add_u64 v[84:85], v[228:229], 0, s[70:71]
	v_add_co_u32_e32 v92, vcc, s59, v88
	global_load_dwordx4 v[80:83], v[84:85], off offset:2048
	s_nop 0
	global_load_dwordx4 v[84:87], v[84:85], off offset:2176
	v_addc_co_u32_e32 v93, vcc, 0, v89, vcc
	global_load_dwordx4 v[88:91], v[88:89], off
	s_nop 0
	global_load_dwordx4 v[96:99], v[92:93], off
	v_mfma_f32_32x32x16_bf16 v[48:63], v[108:111], v[164:167], v[48:63]
	ds_read_b64_tr_b16 v[108:109], v177 offset:47168
	ds_read_b64_tr_b16 v[110:111], v177 offset:49728
	v_exp_f32_e32 v131, v131
	v_exp_f32_e32 v132, v132
	v_exp_f32_e32 v133, v133
	ds_read_b128 v[92:95], v244
	ds_read_b128 v[212:215], v244 offset:32
	ds_read_b128 v[216:219], v244 offset:4608
	ds_read_b128 v[208:211], v244 offset:4640
	v_mfma_f32_32x32x16_bf16 v[32:47], v[104:107], v[164:167], v[32:47]
	ds_read_b64_tr_b16 v[104:105], v177 offset:47232
	ds_read_b64_tr_b16 v[106:107], v177 offset:49792
	v_exp_f32_e32 v134, v134
	v_exp_f32_e32 v135, v135
	v_exp_f32_e32 v136, v136
	ds_read_b128 v[204:207], v244 offset:64
	ds_read_b128 v[196:199], v244 offset:96
	ds_read_b128 v[200:203], v244 offset:4672
	ds_read_b128 v[192:195], v244 offset:4704
	v_mfma_f32_32x32x16_bf16 v[16:31], v[100:103], v[164:167], v[16:31]
	ds_read_b64_tr_b16 v[100:101], v177 offset:47296
	ds_read_b64_tr_b16 v[102:103], v177 offset:49856
	v_exp_f32_e32 v137, v137
	v_exp_f32_e32 v138, v138
	v_exp_f32_e32 v139, v139
	s_waitcnt lgkmcnt(14)
	v_mfma_f32_32x32x16_bf16 v[0:15], v[220:223], v[168:171], v[0:15]
	ds_read_b64_tr_b16 v[220:221], v177 offset:52224
	ds_read_b64_tr_b16 v[222:223], v177 offset:54784
	v_exp_f32_e32 v140, v140
	v_exp_f32_e32 v141, v141
	v_exp_f32_e32 v142, v142
	s_waitcnt lgkmcnt(14)
	v_mfma_f32_32x32x16_bf16 v[48:63], v[108:111], v[168:171], v[48:63]
	ds_read_b64_tr_b16 v[108:109], v177 offset:52288
	ds_read_b64_tr_b16 v[110:111], v177 offset:54848
	v_exp_f32_e32 v143, v143
	v_exp_f32_e32 v112, v112
	v_exp_f32_e32 v113, v113
	s_waitcnt lgkmcnt(10)
	v_mfma_f32_32x32x16_bf16 v[32:47], v[104:107], v[168:171], v[32:47]
	ds_read_b64_tr_b16 v[104:105], v177 offset:52352
	ds_read_b64_tr_b16 v[106:107], v177 offset:54912
	v_exp_f32_e32 v114, v114
	v_exp_f32_e32 v115, v115
	v_exp_f32_e32 v116, v116
	s_waitcnt lgkmcnt(6)
	v_mfma_f32_32x32x16_bf16 v[16:31], v[100:103], v[168:171], v[16:31]
	ds_read_b64_tr_b16 v[100:101], v177 offset:52416
	ds_read_b64_tr_b16 v[102:103], v177 offset:54976
	v_exp_f32_e32 v117, v117
	v_exp_f32_e32 v118, v118
	v_exp_f32_e32 v119, v119
	s_waitcnt lgkmcnt(6)
	v_mfma_f32_32x32x16_bf16 v[0:15], v[220:223], v[172:175], v[0:15]
	v_exp_f32_e32 v120, v120
	v_exp_f32_e32 v121, v121
	s_waitcnt lgkmcnt(4)
	v_mfma_f32_32x32x16_bf16 v[48:63], v[108:111], v[172:175], v[48:63]
	v_exp_f32_e32 v122, v122
	v_exp_f32_e32 v123, v123
	s_waitcnt lgkmcnt(2)
	v_mfma_f32_32x32x16_bf16 v[32:47], v[104:107], v[172:175], v[32:47]
	v_exp_f32_e32 v124, v124
	v_exp_f32_e32 v125, v125
	s_waitcnt lgkmcnt(0)
	v_mfma_f32_32x32x16_bf16 v[16:31], v[100:103], v[172:175], v[16:31]
	v_exp_f32_e32 v126, v126
	v_exp_f32_e32 v127, v127
	s_setprio 0
	v_cmp_neq_f32_e32 vcc, 1.0, v176
	s_cbranch_vccz .LBB0_462
	v_pk_mul_f32 v[14:15], v[176:177], v[14:15] op_sel_hi:[0,1]
	v_pk_mul_f32 v[12:13], v[176:177], v[12:13] op_sel_hi:[0,1]
	v_pk_mul_f32 v[10:11], v[176:177], v[10:11] op_sel_hi:[0,1]
	v_pk_mul_f32 v[8:9], v[176:177], v[8:9] op_sel_hi:[0,1]
	v_pk_mul_f32 v[6:7], v[176:177], v[6:7] op_sel_hi:[0,1]
	v_pk_mul_f32 v[4:5], v[176:177], v[4:5] op_sel_hi:[0,1]
	v_pk_mul_f32 v[2:3], v[176:177], v[2:3] op_sel_hi:[0,1]
	v_pk_mul_f32 v[0:1], v[176:177], v[0:1] op_sel_hi:[0,1]
	v_pk_mul_f32 v[62:63], v[176:177], v[62:63] op_sel_hi:[0,1]
	v_pk_mul_f32 v[60:61], v[176:177], v[60:61] op_sel_hi:[0,1]
	v_pk_mul_f32 v[58:59], v[176:177], v[58:59] op_sel_hi:[0,1]
	v_pk_mul_f32 v[56:57], v[176:177], v[56:57] op_sel_hi:[0,1]
	v_pk_mul_f32 v[54:55], v[176:177], v[54:55] op_sel_hi:[0,1]
	v_pk_mul_f32 v[52:53], v[176:177], v[52:53] op_sel_hi:[0,1]
	v_pk_mul_f32 v[50:51], v[176:177], v[50:51] op_sel_hi:[0,1]
	v_pk_mul_f32 v[48:49], v[176:177], v[48:49] op_sel_hi:[0,1]
	v_pk_mul_f32 v[46:47], v[176:177], v[46:47] op_sel_hi:[0,1]
	v_pk_mul_f32 v[44:45], v[176:177], v[44:45] op_sel_hi:[0,1]
	v_pk_mul_f32 v[42:43], v[176:177], v[42:43] op_sel_hi:[0,1]
	v_pk_mul_f32 v[40:41], v[176:177], v[40:41] op_sel_hi:[0,1]
	v_pk_mul_f32 v[38:39], v[176:177], v[38:39] op_sel_hi:[0,1]
	v_pk_mul_f32 v[36:37], v[176:177], v[36:37] op_sel_hi:[0,1]
	v_pk_mul_f32 v[34:35], v[176:177], v[34:35] op_sel_hi:[0,1]
	v_pk_mul_f32 v[32:33], v[176:177], v[32:33] op_sel_hi:[0,1]
	v_pk_mul_f32 v[30:31], v[176:177], v[30:31] op_sel_hi:[0,1]
	v_pk_mul_f32 v[28:29], v[176:177], v[28:29] op_sel_hi:[0,1]
	v_pk_mul_f32 v[26:27], v[176:177], v[26:27] op_sel_hi:[0,1]
	v_pk_mul_f32 v[24:25], v[176:177], v[24:25] op_sel_hi:[0,1]
	v_pk_mul_f32 v[22:23], v[176:177], v[22:23] op_sel_hi:[0,1]
	v_pk_mul_f32 v[20:21], v[176:177], v[20:21] op_sel_hi:[0,1]
	v_pk_mul_f32 v[18:19], v[176:177], v[18:19] op_sel_hi:[0,1]
	v_pk_mul_f32 v[16:17], v[176:177], v[16:17] op_sel_hi:[0,1]
.LBB0_462:
	s_add_i32 s18, s16, 0x5000
	s_cmpk_lg_u32 s16, 0xf000
	s_cselect_b32 s16, s18, 0
	s_add_i32 s18, s17, 0x5000
	s_cmpk_lg_u32 s17, 0xf000
	s_cselect_b32 s17, s18, 0
	s_waitcnt vmcnt(3)
	ds_write_b128 v243, v[80:83] offset:18432
	s_waitcnt vmcnt(2)
	ds_write_b128 v243, v[84:87] offset:27648
	v_add_u32_e32 v80, s17, v242
	v_add_u32_e32 v161, s16, v246
	s_waitcnt vmcnt(1)
	ds_write_b128 v80, v[88:91] offset:36864
	s_waitcnt vmcnt(0)
	ds_write_b128 v80, v[96:99] offset:47104
	v_mfma_f32_32x32x16_bf16 v[96:111], v[92:95], v[156:159], v[64:79]
	v_add_f32_e32 v80, v128, v130
	v_add_f32_e32 v81, v129, v131
	v_add_f32_e32 v80, v132, v80
	v_add_f32_e32 v81, v133, v81
	v_cvt_pk_bf16_f32 v176, v128, v129
	v_cvt_pk_bf16_f32 v177, v130, v131
	s_nop 0
	v_add_f32_e32 v80, v134, v80
	v_add_f32_e32 v81, v135, v81
	v_add_f32_e32 v128, v136, v80
	v_add_f32_e32 v129, v137, v81
	v_mfma_f32_32x32x16_bf16 v[80:95], v[216:219], v[156:159], v[64:79]
	v_cvt_pk_bf16_f32 v178, v132, v133
	v_cvt_pk_bf16_f32 v179, v134, v135
	v_mfma_f32_32x32x16_bf16 v[96:111], v[212:215], v[152:155], v[96:111]
	v_add_f32_e32 v128, v138, v128
	v_add_f32_e32 v129, v139, v129
	v_add_f32_e32 v128, v140, v128
	v_add_f32_e32 v129, v141, v129
	v_cvt_pk_bf16_f32 v180, v136, v137
	v_cvt_pk_bf16_f32 v181, v138, v139
	v_mfma_f32_32x32x16_bf16 v[80:95], v[208:211], v[152:155], v[80:95]
	v_add_f32_e32 v128, v142, v128
	v_add_f32_e32 v129, v143, v129
	v_add_f32_e32 v128, v112, v128
	v_add_f32_e32 v129, v113, v129
	v_cvt_pk_bf16_f32 v182, v140, v141
	v_cvt_pk_bf16_f32 v183, v142, v143
	v_mfma_f32_32x32x16_bf16 v[96:111], v[204:207], v[148:151], v[96:111]
	ds_read_b64_tr_b16 v[140:141], v161 offset:36864
	ds_read_b64_tr_b16 v[142:143], v161 offset:39424
	v_add_f32_e32 v128, v114, v128
	v_add_f32_e32 v129, v115, v129
	v_add_f32_e32 v128, v116, v128
	v_add_f32_e32 v129, v117, v129
	v_cvt_pk_bf16_f32 v184, v112, v113
	v_cvt_pk_bf16_f32 v185, v114, v115
	v_mfma_f32_32x32x16_bf16 v[80:95], v[200:203], v[148:151], v[80:95]
	ds_read_b64_tr_b16 v[136:137], v161 offset:36928
	ds_read_b64_tr_b16 v[138:139], v161 offset:39488
	v_add_f32_e32 v112, v118, v128
	v_add_f32_e32 v113, v119, v129
	v_add_f32_e32 v112, v120, v112
	v_add_f32_e32 v113, v121, v113
	v_cvt_pk_bf16_f32 v186, v116, v117
	v_cvt_pk_bf16_f32 v187, v118, v119
	v_mfma_f32_32x32x16_bf16 v[96:111], v[196:199], v[144:147], v[96:111]
	ds_read_b64_tr_b16 v[132:133], v161 offset:36992
	ds_read_b64_tr_b16 v[134:135], v161 offset:39552
	v_add_f32_e32 v112, v122, v112
	v_add_f32_e32 v113, v123, v113
	v_add_f32_e32 v112, v124, v112
	v_add_f32_e32 v113, v125, v113
	v_cvt_pk_bf16_f32 v188, v120, v121
	v_cvt_pk_bf16_f32 v189, v122, v123
	v_mfma_f32_32x32x16_bf16 v[80:95], v[192:195], v[144:147], v[80:95]
	ds_read_b64_tr_b16 v[128:129], v161 offset:37056
	ds_read_b64_tr_b16 v[130:131], v161 offset:39616
	v_add_f32_e32 v112, v126, v112
	v_add_f32_e32 v113, v127, v113
	v_add_f32_e32 v112, 0, v112
	v_add_f32_e32 v113, 0, v113
	v_cvt_pk_bf16_f32 v190, v124, v125
	v_cvt_pk_bf16_f32 v191, v126, v127
	s_nop 0
	v_add_f32_e32 v112, v112, v113
	v_add_f32_e32 v247, v247, v112
	s_waitcnt lgkmcnt(6)
	v_mfma_f32_32x32x16_bf16 v[0:15], v[140:143], v[176:179], v[0:15]
	ds_read_b64_tr_b16 v[140:141], v161 offset:41984
	ds_read_b64_tr_b16 v[142:143], v161 offset:44544
	v_max3_f32 v113, v96, v97, v80
	v_max3_f32 v114, v98, v99, v81
	v_max3_f32 v113, v113, v82, v83
	v_max3_f32 v114, v114, v102, v103
	v_max3_f32 v113, v113, v100, v101
	s_waitcnt lgkmcnt(6)
	v_mfma_f32_32x32x16_bf16 v[48:63], v[136:139], v[176:179], v[48:63]
	ds_read_b64_tr_b16 v[136:137], v161 offset:42048
	ds_read_b64_tr_b16 v[138:139], v161 offset:44608
	v_max3_f32 v114, v114, v86, v87
	v_max3_f32 v113, v113, v84, v85
	v_max3_f32 v114, v114, v106, v107
	v_max3_f32 v113, v113, v104, v105
	s_waitcnt lgkmcnt(6)
	v_mfma_f32_32x32x16_bf16 v[32:47], v[132:135], v[176:179], v[32:47]
	ds_read_b64_tr_b16 v[132:133], v161 offset:42112
	ds_read_b64_tr_b16 v[134:135], v161 offset:44672
	v_max3_f32 v114, v114, v90, v91
	v_max3_f32 v113, v113, v88, v89
	v_max3_f32 v114, v114, v110, v111
	v_max3_f32 v113, v113, v108, v109
	s_waitcnt lgkmcnt(6)
	v_mfma_f32_32x32x16_bf16 v[16:31], v[128:131], v[176:179], v[16:31]
	ds_read_b64_tr_b16 v[128:129], v161 offset:42176
	ds_read_b64_tr_b16 v[130:131], v161 offset:44736
	v_max3_f32 v114, v114, v94, v95
	v_max3_f32 v113, v113, v92, v93
	v_max_f32_e32 v112, v113, v114
	v_mov_b32_e32 v113, v112
	s_nop 1
	v_permlane32_swap_b32_e32 v112, v113
	v_max_f32_e32 v112, v112, v113
	v_cmp_lt_f32_e32 vcc, s61, v112
	s_cbranch_vccnz .LBB0_467
	v_mov_b32_e32 v160, 1.0
.LBB0_464:
	s_and_b32 s18, s4, 0x7c0
	s_mul_i32 s70, s18, 0x2800
	v_lshl_add_u64 v[120:121], v[226:227], 0, s[70:71]
	v_add_co_u32_e32 v124, vcc, s59, v120
	s_waitcnt lgkmcnt(0)
	s_barrier
	s_setprio 1
	v_mfma_f32_32x32x16_bf16 v[0:15], v[140:143], v[180:183], v[0:15]
	ds_read_b64_tr_b16 v[140:141], v161 offset:47104
	ds_read_b64_tr_b16 v[142:143], v161 offset:49664
	v_exp_f32_e32 v96, v96
	v_exp_f32_e32 v97, v97
	v_exp_f32_e32 v98, v98
	v_lshl_add_u64 v[116:117], v[228:229], 0, s[70:71]
	v_addc_co_u32_e32 v125, vcc, 0, v121, vcc
	global_load_dwordx4 v[112:115], v[116:117], off offset:2048
	s_nop 0
	global_load_dwordx4 v[116:119], v[116:117], off offset:2176
	s_nop 0
	global_load_dwordx4 v[120:123], v[120:121], off
	s_nop 0
	global_load_dwordx4 v[124:127], v[124:125], off
	v_mfma_f32_32x32x16_bf16 v[48:63], v[136:139], v[180:183], v[48:63]
	ds_read_b64_tr_b16 v[136:137], v161 offset:47168
	ds_read_b64_tr_b16 v[138:139], v161 offset:49728
	v_exp_f32_e32 v99, v99
	v_exp_f32_e32 v100, v100
	v_exp_f32_e32 v101, v101
	ds_read_b128 v[220:223], v244 offset:18432
	ds_read_b128 v[212:215], v244 offset:18464
	ds_read_b128 v[216:219], v244 offset:23040
	ds_read_b128 v[208:211], v244 offset:23072
	v_mfma_f32_32x32x16_bf16 v[32:47], v[132:135], v[180:183], v[32:47]
	ds_read_b64_tr_b16 v[132:133], v161 offset:47232
	ds_read_b64_tr_b16 v[134:135], v161 offset:49792
	v_exp_f32_e32 v102, v102
	v_exp_f32_e32 v103, v103
	v_exp_f32_e32 v104, v104
	ds_read_b128 v[204:207], v244 offset:18496
	ds_read_b128 v[196:199], v244 offset:18528
	ds_read_b128 v[200:203], v244 offset:23104
	ds_read_b128 v[192:195], v244 offset:23136
	v_mfma_f32_32x32x16_bf16 v[16:31], v[128:131], v[180:183], v[16:31]
	ds_read_b64_tr_b16 v[128:129], v161 offset:47296
	ds_read_b64_tr_b16 v[130:131], v161 offset:49856
	v_exp_f32_e32 v105, v105
	v_exp_f32_e32 v106, v106
	v_exp_f32_e32 v107, v107
	s_waitcnt lgkmcnt(14)
	v_mfma_f32_32x32x16_bf16 v[0:15], v[140:143], v[184:187], v[0:15]
	ds_read_b64_tr_b16 v[140:141], v161 offset:52224
	ds_read_b64_tr_b16 v[142:143], v161 offset:54784
	v_exp_f32_e32 v108, v108
	v_exp_f32_e32 v109, v109
	v_exp_f32_e32 v110, v110
	s_waitcnt lgkmcnt(14)
	v_mfma_f32_32x32x16_bf16 v[48:63], v[136:139], v[184:187], v[48:63]
	ds_read_b64_tr_b16 v[136:137], v161 offset:52288
	ds_read_b64_tr_b16 v[138:139], v161 offset:54848
	v_exp_f32_e32 v111, v111
	v_exp_f32_e32 v80, v80
	v_exp_f32_e32 v81, v81
	s_waitcnt lgkmcnt(10)
	v_mfma_f32_32x32x16_bf16 v[32:47], v[132:135], v[184:187], v[32:47]
	ds_read_b64_tr_b16 v[132:133], v161 offset:52352
	ds_read_b64_tr_b16 v[134:135], v161 offset:54912
	v_exp_f32_e32 v82, v82
	v_exp_f32_e32 v83, v83
	v_exp_f32_e32 v84, v84
	s_waitcnt lgkmcnt(6)
	v_mfma_f32_32x32x16_bf16 v[16:31], v[128:131], v[184:187], v[16:31]
	ds_read_b64_tr_b16 v[128:129], v161 offset:52416
	ds_read_b64_tr_b16 v[130:131], v161 offset:54976
	v_exp_f32_e32 v85, v85
	v_exp_f32_e32 v86, v86
	v_exp_f32_e32 v87, v87
	s_waitcnt lgkmcnt(6)
	v_mfma_f32_32x32x16_bf16 v[0:15], v[140:143], v[188:191], v[0:15]
	v_exp_f32_e32 v88, v88
	v_exp_f32_e32 v89, v89
	s_waitcnt lgkmcnt(4)
	v_mfma_f32_32x32x16_bf16 v[48:63], v[136:139], v[188:191], v[48:63]
	v_exp_f32_e32 v90, v90
	v_exp_f32_e32 v91, v91
	s_waitcnt lgkmcnt(2)
	v_mfma_f32_32x32x16_bf16 v[32:47], v[132:135], v[188:191], v[32:47]
	v_exp_f32_e32 v92, v92
	v_exp_f32_e32 v93, v93
	s_waitcnt lgkmcnt(0)
	v_mfma_f32_32x32x16_bf16 v[16:31], v[128:131], v[188:191], v[16:31]
	v_exp_f32_e32 v94, v94
	v_exp_f32_e32 v95, v95
	s_setprio 0
	v_cmp_neq_f32_e32 vcc, 1.0, v160
	s_cbranch_vccz .LBB0_457
	v_pk_mul_f32 v[14:15], v[160:161], v[14:15] op_sel_hi:[0,1]
	v_pk_mul_f32 v[12:13], v[160:161], v[12:13] op_sel_hi:[0,1]
	v_pk_mul_f32 v[10:11], v[160:161], v[10:11] op_sel_hi:[0,1]
	v_pk_mul_f32 v[8:9], v[160:161], v[8:9] op_sel_hi:[0,1]
	v_pk_mul_f32 v[6:7], v[160:161], v[6:7] op_sel_hi:[0,1]
	v_pk_mul_f32 v[4:5], v[160:161], v[4:5] op_sel_hi:[0,1]
	v_pk_mul_f32 v[2:3], v[160:161], v[2:3] op_sel_hi:[0,1]
	v_pk_mul_f32 v[0:1], v[160:161], v[0:1] op_sel_hi:[0,1]
	v_pk_mul_f32 v[62:63], v[160:161], v[62:63] op_sel_hi:[0,1]
	v_pk_mul_f32 v[60:61], v[160:161], v[60:61] op_sel_hi:[0,1]
	v_pk_mul_f32 v[58:59], v[160:161], v[58:59] op_sel_hi:[0,1]
	v_pk_mul_f32 v[56:57], v[160:161], v[56:57] op_sel_hi:[0,1]
	v_pk_mul_f32 v[54:55], v[160:161], v[54:55] op_sel_hi:[0,1]
	v_pk_mul_f32 v[52:53], v[160:161], v[52:53] op_sel_hi:[0,1]
	v_pk_mul_f32 v[50:51], v[160:161], v[50:51] op_sel_hi:[0,1]
	v_pk_mul_f32 v[48:49], v[160:161], v[48:49] op_sel_hi:[0,1]
	v_pk_mul_f32 v[46:47], v[160:161], v[46:47] op_sel_hi:[0,1]
	v_pk_mul_f32 v[44:45], v[160:161], v[44:45] op_sel_hi:[0,1]
	v_pk_mul_f32 v[42:43], v[160:161], v[42:43] op_sel_hi:[0,1]
	v_pk_mul_f32 v[40:41], v[160:161], v[40:41] op_sel_hi:[0,1]
	v_pk_mul_f32 v[38:39], v[160:161], v[38:39] op_sel_hi:[0,1]
	v_pk_mul_f32 v[36:37], v[160:161], v[36:37] op_sel_hi:[0,1]
	v_pk_mul_f32 v[34:35], v[160:161], v[34:35] op_sel_hi:[0,1]
	v_pk_mul_f32 v[32:33], v[160:161], v[32:33] op_sel_hi:[0,1]
	v_pk_mul_f32 v[30:31], v[160:161], v[30:31] op_sel_hi:[0,1]
	v_pk_mul_f32 v[28:29], v[160:161], v[28:29] op_sel_hi:[0,1]
	v_pk_mul_f32 v[26:27], v[160:161], v[26:27] op_sel_hi:[0,1]
	v_pk_mul_f32 v[24:25], v[160:161], v[24:25] op_sel_hi:[0,1]
	v_pk_mul_f32 v[22:23], v[160:161], v[22:23] op_sel_hi:[0,1]
	v_pk_mul_f32 v[20:21], v[160:161], v[20:21] op_sel_hi:[0,1]
	v_pk_mul_f32 v[18:19], v[160:161], v[18:19] op_sel_hi:[0,1]
	v_pk_mul_f32 v[16:17], v[160:161], v[16:17] op_sel_hi:[0,1]
	s_branch .LBB0_457
